# P0 weight-transpose loops: all 32 loads of an item in flight before first wait
# speedup vs baseline: 1.0107x; 1.0095x over previous
; #define LAS __attribute__((address_space(3)))
; __device__ __forceinline__ unsigned cvtpk(float lo, float hi) { unsigned r; asm volatile("v_cvt_pk_bf16_f32 %0, %1, %2" : "=v"(r) : "v"(lo), "v"(hi)); return r; }
; __device__ __forceinline__ void transpose_item(const float* W, int K, int N, bf16_t* WT, LAS float* scr, int item, int lane, int perm_below) {
;     const int nblk = N / 32, kb = item / nblk, nb = item % nblk, k0 = 64 * kb, n0 = 32 * nb;
; #pragma unroll 8
;     for (int i = 0; i < 32; ++i) { const int kk = 2 * i + (lane >> 5); scr[kk * 33 + (lane & 31)] = __builtin_nontemporal_load(W + (size_t)(k0 + kk) * N + n0 + (lane & 31)); }
;     asm volatile("s_waitcnt lgkmcnt(0)" ::: "memory");
;     const int c = lane & 7; const bool pr = n0 < perm_below;
; #pragma unroll
;     for (int j = 0; j < 4; ++j) { const int n = (lane >> 3) + 8 * j; const int ns = pr ? pg8::perm32inv(n) : n; const LAS float* s = scr + (8 * c) * 33 + ns;
;         u32x4 o; o.x = cvtpk(s[0 * 33], s[1 * 33]); o.y = cvtpk(s[2 * 33], s[3 * 33]); o.z = cvtpk(s[4 * 33], s[5 * 33]); o.w = cvtpk(s[6 * 33], s[7 * 33]);
;         *(u32x4*)(WT + (size_t)(n0 + n) * K + k0 + 8 * c) = o; }
;     asm volatile("s_waitcnt lgkmcnt(0)" ::: "memory");
; }
; __global__ void __launch_bounds__(512, 2) fwd_megakernel(Params p) {
;     ...
;         for (int it = gw; it < I_IN + I_OUT; it += NGW) {
;             if (it < I_IN) transpose_item(p.w_in, DM, INC, WinT, scr, it, lane, 2048);
;             else transpose_item(p.w_out, DM, DM, WoutT, scr, it - I_IN, lane, 0);
.LBB0_39:
	s_cmpk_gt_i32 s5, 0x1fff
	s_mov_b64 s[6:7], -1
	s_cbranch_scc0 .LBB0_43
	s_lshl_b32 s0, s12, 2
	s_and_b32 s6, s14, 0xffc0
	s_and_b32 s0, s0, 0x1f80
	v_or_b32_e32 v4, s6, v39
	v_lshl_or_b32 v4, v4, 13, s0
	v_lshl_add_u64 v[12:13], v[2:3], 0, v[4:5]
	v_or_b32_e32 v4, s6, v40
	v_lshl_or_b32 v4, v4, 13, s0
	v_lshl_add_u64 v[14:15], v[2:3], 0, v[4:5]
	v_or_b32_e32 v4, s6, v41
	v_lshl_or_b32 v4, v4, 13, s0
	v_lshl_add_u64 v[16:17], v[2:3], 0, v[4:5]
	v_or_b32_e32 v4, s6, v42
	v_lshl_or_b32 v4, v4, 13, s0
	v_lshl_add_u64 v[18:19], v[2:3], 0, v[4:5]
	v_or_b32_e32 v4, s6, v43
	v_lshl_or_b32 v4, v4, 13, s0
	v_lshl_add_u64 v[20:21], v[2:3], 0, v[4:5]
	v_or_b32_e32 v4, s6, v44
	v_lshl_or_b32 v4, v4, 13, s0
	v_lshl_add_u64 v[22:23], v[2:3], 0, v[4:5]
	v_or_b32_e32 v4, s6, v45
	v_lshl_or_b32 v4, v4, 13, s0
	v_lshl_add_u64 v[24:25], v[2:3], 0, v[4:5]
	v_or_b32_e32 v4, s6, v28
	v_lshl_or_b32 v4, v4, 13, s0
	v_lshl_add_u64 v[26:27], v[2:3], 0, v[4:5]
	s_mov_b64 s[6:7], 0
	v_mov_b32_e32 v4, v38
	v_lshl_add_u64 v[46:47], v[26:27], 0, s[6:7]
	v_lshl_add_u64 v[48:49], v[24:25], 0, s[6:7]
	v_lshl_add_u64 v[50:51], v[22:23], 0, s[6:7]
	v_lshl_add_u64 v[52:53], v[20:21], 0, s[6:7]
	v_lshl_add_u64 v[54:55], v[18:19], 0, s[6:7]
	v_lshl_add_u64 v[56:57], v[16:17], 0, s[6:7]
	v_lshl_add_u64 v[58:59], v[14:15], 0, s[6:7]
	v_lshl_add_u64 v[60:61], v[12:13], 0, s[6:7]
	global_load_dword v70, v[46:47], off nt
	global_load_dword v71, v[48:49], off nt
	global_load_dword v72, v[50:51], off nt
	global_load_dword v73, v[52:53], off nt
	global_load_dword v74, v[54:55], off nt
	global_load_dword v75, v[56:57], off nt
	global_load_dword v76, v[58:59], off nt
	global_load_dword v77, v[60:61], off nt
	s_add_u32 s6, s6, 0x20000
	s_addc_u32 s7, s7, 0
	v_lshl_add_u64 v[46:47], v[26:27], 0, s[6:7]
	v_lshl_add_u64 v[48:49], v[24:25], 0, s[6:7]
	v_lshl_add_u64 v[50:51], v[22:23], 0, s[6:7]
	v_lshl_add_u64 v[52:53], v[20:21], 0, s[6:7]
	v_lshl_add_u64 v[54:55], v[18:19], 0, s[6:7]
	v_lshl_add_u64 v[56:57], v[16:17], 0, s[6:7]
	v_lshl_add_u64 v[58:59], v[14:15], 0, s[6:7]
	v_lshl_add_u64 v[60:61], v[12:13], 0, s[6:7]
	global_load_dword v78, v[46:47], off nt
	global_load_dword v79, v[48:49], off nt
	global_load_dword v80, v[50:51], off nt
	global_load_dword v81, v[52:53], off nt
	global_load_dword v82, v[54:55], off nt
	global_load_dword v83, v[56:57], off nt
	global_load_dword v84, v[58:59], off nt
	global_load_dword v85, v[60:61], off nt
	s_add_u32 s6, s6, 0x20000
	s_addc_u32 s7, s7, 0
	v_lshl_add_u64 v[46:47], v[26:27], 0, s[6:7]
	v_lshl_add_u64 v[48:49], v[24:25], 0, s[6:7]
	v_lshl_add_u64 v[50:51], v[22:23], 0, s[6:7]
	v_lshl_add_u64 v[52:53], v[20:21], 0, s[6:7]
	v_lshl_add_u64 v[54:55], v[18:19], 0, s[6:7]
	v_lshl_add_u64 v[56:57], v[16:17], 0, s[6:7]
	v_lshl_add_u64 v[58:59], v[14:15], 0, s[6:7]
	v_lshl_add_u64 v[60:61], v[12:13], 0, s[6:7]
	global_load_dword v86, v[46:47], off nt
	global_load_dword v87, v[48:49], off nt
	global_load_dword v88, v[50:51], off nt
	global_load_dword v89, v[52:53], off nt
	global_load_dword v90, v[54:55], off nt
	global_load_dword v91, v[56:57], off nt
	global_load_dword v92, v[58:59], off nt
	global_load_dword v93, v[60:61], off nt
	s_add_u32 s6, s6, 0x20000
	s_addc_u32 s7, s7, 0
	v_lshl_add_u64 v[46:47], v[26:27], 0, s[6:7]
	v_lshl_add_u64 v[48:49], v[24:25], 0, s[6:7]
	v_lshl_add_u64 v[50:51], v[22:23], 0, s[6:7]
	v_lshl_add_u64 v[52:53], v[20:21], 0, s[6:7]
	v_lshl_add_u64 v[54:55], v[18:19], 0, s[6:7]
	v_lshl_add_u64 v[56:57], v[16:17], 0, s[6:7]
	v_lshl_add_u64 v[58:59], v[14:15], 0, s[6:7]
	v_lshl_add_u64 v[60:61], v[12:13], 0, s[6:7]
	global_load_dword v94, v[46:47], off nt
	global_load_dword v95, v[48:49], off nt
	global_load_dword v96, v[50:51], off nt
	global_load_dword v97, v[52:53], off nt
	global_load_dword v98, v[54:55], off nt
	global_load_dword v99, v[56:57], off nt
	global_load_dword v100, v[58:59], off nt
	global_load_dword v101, v[60:61], off nt
	s_add_u32 s6, s6, 0x20000
	s_addc_u32 s7, s7, 0
	v_add_u32_e32 v46, 0x400, v4
	s_waitcnt vmcnt(30)
	ds_write2_b32 v4, v70, v71 offset1:66
	s_waitcnt vmcnt(28)
	ds_write2_b32 v4, v72, v73 offset0:132 offset1:198
	s_waitcnt vmcnt(26)
	ds_write2_b32 v46, v74, v75 offset0:8 offset1:74
	s_waitcnt vmcnt(24)
	ds_write2_b32 v46, v76, v77 offset0:140 offset1:206
	v_add_u32_e32 v4, 0x840, v4
	v_add_u32_e32 v46, 0x400, v4
	s_waitcnt vmcnt(22)
	ds_write2_b32 v4, v78, v79 offset1:66
	s_waitcnt vmcnt(20)
	ds_write2_b32 v4, v80, v81 offset0:132 offset1:198
	s_waitcnt vmcnt(18)
	ds_write2_b32 v46, v82, v83 offset0:8 offset1:74
	s_waitcnt vmcnt(16)
	ds_write2_b32 v46, v84, v85 offset0:140 offset1:206
	v_add_u32_e32 v4, 0x840, v4
	v_add_u32_e32 v46, 0x400, v4
	s_waitcnt vmcnt(14)
	ds_write2_b32 v4, v86, v87 offset1:66
	s_waitcnt vmcnt(12)
	ds_write2_b32 v4, v88, v89 offset0:132 offset1:198
	s_waitcnt vmcnt(10)
	ds_write2_b32 v46, v90, v91 offset0:8 offset1:74
	s_waitcnt vmcnt(8)
	ds_write2_b32 v46, v92, v93 offset0:140 offset1:206
	v_add_u32_e32 v4, 0x840, v4
	v_add_u32_e32 v46, 0x400, v4
	s_waitcnt vmcnt(6)
	ds_write2_b32 v4, v94, v95 offset1:66
	s_waitcnt vmcnt(4)
	ds_write2_b32 v4, v96, v97 offset0:132 offset1:198
	s_waitcnt vmcnt(2)
	ds_write2_b32 v46, v98, v99 offset0:8 offset1:74
	s_waitcnt vmcnt(0)
	ds_write2_b32 v46, v100, v101 offset0:140 offset1:206
	v_add_u32_e32 v4, 0x840, v4
	s_waitcnt lgkmcnt(0)
	s_add_i32 s0, s5, 0xe000
	s_lshl_b32 s6, s5, 5
	ds_read2_b32 v[12:13], v30 offset1:33
	s_and_b32 s0, s0, 0xffc0
	s_and_b32 s6, s6, 0x7e0
	s_waitcnt lgkmcnt(0)
	v_cvt_pk_bf16_f32 v12, v12, v13
	ds_read2_b32 v[14:15], v30 offset0:66 offset1:99
	s_lshl_b32 s0, s0, 1
	v_or_b32_e32 v4, s6, v29
	s_waitcnt lgkmcnt(0)
; #define LAS __attribute__((address_space(3)))
; __device__ __forceinline__ unsigned cvtpk(float lo, float hi) { unsigned r; asm volatile("v_cvt_pk_bf16_f32 %0, %1, %2" : "=v"(r) : "v"(lo), "v"(hi)); return r; }
; __device__ __forceinline__ void transpose_item(const float* W, int K, int N, bf16_t* WT, LAS float* scr, int item, int lane, int perm_below) {
;     const int nblk = N / 32, kb = item / nblk, nb = item % nblk, k0 = 64 * kb, n0 = 32 * nb;
; #pragma unroll 8
;     for (int i = 0; i < 32; ++i) { const int kk = 2 * i + (lane >> 5); scr[kk * 33 + (lane & 31)] = __builtin_nontemporal_load(W + (size_t)(k0 + kk) * N + n0 + (lane & 31)); }
;     ...
;     const int c = lane & 7; const bool pr = n0 < perm_below;
; #pragma unroll
;     for (int j = 0; j < 4; ++j) { const int n = (lane >> 3) + 8 * j; const int ns = pr ? pg8::perm32inv(n) : n; const LAS float* s = scr + (8 * c) * 33 + ns;
;         u32x4 o; o.x = cvtpk(s[0 * 33], s[1 * 33]); o.y = cvtpk(s[2 * 33], s[3 * 33]); o.z = cvtpk(s[4 * 33], s[5 * 33]); o.w = cvtpk(s[6 * 33], s[7 * 33]);
;         *(u32x4*)(WT + (size_t)(n0 + n) * K + k0 + 8 * c) = o; }
	v_cvt_pk_bf16_f32 v13, v14, v15
	ds_read2_b32 v[14:15], v30 offset0:132 offset1:165
	v_lshl_add_u64 v[18:19], v[6:7], 0, s[0:1]
	v_lshlrev_b32_e32 v4, 12, v4
	s_waitcnt lgkmcnt(0)
	v_cvt_pk_bf16_f32 v14, v14, v15
	ds_read2_b32 v[16:17], v30 offset0:198 offset1:231
	s_waitcnt lgkmcnt(0)
	v_cvt_pk_bf16_f32 v15, v16, v17
	v_lshl_add_u64 v[20:21], v[18:19], 0, v[4:5]
	ds_read2_b32 v[16:17], v30 offset0:8 offset1:41
	global_store_dwordx4 v[20:21], v[12:15], off
	v_or_b32_e32 v4, s6, v31
	v_lshlrev_b32_e32 v4, 12, v4
	s_waitcnt lgkmcnt(0)
	v_cvt_pk_bf16_f32 v12, v16, v17
	ds_read2_b32 v[14:15], v30 offset0:74 offset1:107
	s_waitcnt lgkmcnt(0)
	v_cvt_pk_bf16_f32 v13, v14, v15
	ds_read2_b32 v[14:15], v30 offset0:140 offset1:173
	s_waitcnt lgkmcnt(0)
	v_cvt_pk_bf16_f32 v14, v14, v15
	ds_read2_b32 v[16:17], v30 offset0:206 offset1:239
	s_waitcnt lgkmcnt(0)
	v_cvt_pk_bf16_f32 v15, v16, v17
	v_lshl_add_u64 v[20:21], v[18:19], 0, v[4:5]
	ds_read2_b32 v[16:17], v30 offset0:16 offset1:49
	global_store_dwordx4 v[20:21], v[12:15], off
	v_or_b32_e32 v4, s6, v32
	v_lshlrev_b32_e32 v4, 12, v4
	s_waitcnt lgkmcnt(0)
	v_cvt_pk_bf16_f32 v12, v16, v17
	ds_read2_b32 v[14:15], v30 offset0:82 offset1:115
	s_waitcnt lgkmcnt(0)
	v_cvt_pk_bf16_f32 v13, v14, v15
	ds_read2_b32 v[14:15], v30 offset0:148 offset1:181
	s_waitcnt lgkmcnt(0)
	v_cvt_pk_bf16_f32 v14, v14, v15
	ds_read2_b32 v[16:17], v30 offset0:214 offset1:247
	s_waitcnt lgkmcnt(0)
	v_cvt_pk_bf16_f32 v15, v16, v17
	v_lshl_add_u64 v[20:21], v[18:19], 0, v[4:5]
	ds_read2_b32 v[16:17], v30 offset0:24 offset1:57
	global_store_dwordx4 v[20:21], v[12:15], off
	v_or_b32_e32 v4, s6, v33
	v_lshlrev_b32_e32 v4, 12, v4
	s_waitcnt lgkmcnt(0)
	v_cvt_pk_bf16_f32 v12, v16, v17
	ds_read2_b32 v[14:15], v30 offset0:90 offset1:123
	s_waitcnt lgkmcnt(0)
	v_cvt_pk_bf16_f32 v13, v14, v15
	ds_read2_b32 v[14:15], v30 offset0:156 offset1:189
	s_waitcnt lgkmcnt(0)
	v_cvt_pk_bf16_f32 v14, v14, v15
	ds_read2_b32 v[16:17], v30 offset0:222 offset1:255
	s_waitcnt lgkmcnt(0)
	v_cvt_pk_bf16_f32 v15, v16, v17
	v_lshl_add_u64 v[16:17], v[18:19], 0, v[4:5]
	global_store_dwordx4 v[16:17], v[12:15], off
	s_waitcnt lgkmcnt(0)
	s_mov_b64 s[6:7], 0
.LBB0_43:
	s_and_b64 vcc, exec, s[6:7]
	s_cbranch_vccz .LBB0_38
	s_ashr_i32 s0, s5, 31
	s_lshr_b32 s0, s0, 24
	s_add_i32 s0, s5, s0
	s_ashr_i32 s6, s0, 8
	s_and_b32 s0, s0, 0xffffff00
	s_sub_i32 s0, s5, s0
	s_lshl_b32 s8, s6, 6
	s_lshl_b32 s6, s0, 5
	v_or_b32_e32 v12, s8, v39
	v_or_b32_e32 v14, s8, v40
	v_or_b32_e32 v16, s8, v41
	v_or_b32_e32 v18, s8, v42
	v_or_b32_e32 v20, s8, v43
	v_or_b32_e32 v22, s8, v44
	v_or_b32_e32 v24, s8, v45
	v_or_b32_e32 v26, s8, v28
	s_ashr_i32 s7, s6, 31
	v_ashrrev_i32_e32 v13, 31, v12
	v_ashrrev_i32_e32 v15, 31, v14
	v_ashrrev_i32_e32 v17, 31, v16
	v_ashrrev_i32_e32 v19, 31, v18
	v_ashrrev_i32_e32 v21, 31, v20
	v_ashrrev_i32_e32 v23, 31, v22
	v_ashrrev_i32_e32 v25, 31, v24
	v_ashrrev_i32_e32 v27, 31, v26
	v_lshlrev_b64 v[12:13], 15, v[12:13]
	s_lshl_b64 s[10:11], s[6:7], 2
	v_lshlrev_b64 v[14:15], 15, v[14:15]
	v_lshlrev_b64 v[16:17], 15, v[16:17]
	v_lshlrev_b64 v[18:19], 15, v[18:19]
	v_lshlrev_b64 v[20:21], 15, v[20:21]
	v_lshlrev_b64 v[22:23], 15, v[22:23]
	v_lshlrev_b64 v[24:25], 15, v[24:25]
	v_lshlrev_b64 v[26:27], 15, v[26:27]
	v_lshl_add_u64 v[12:13], v[12:13], 0, s[10:11]
	v_lshl_add_u64 v[14:15], v[14:15], 0, s[10:11]
	v_lshl_add_u64 v[16:17], v[16:17], 0, s[10:11]
	v_lshl_add_u64 v[18:19], v[18:19], 0, s[10:11]
	v_lshl_add_u64 v[20:21], v[20:21], 0, s[10:11]
	v_lshl_add_u64 v[22:23], v[22:23], 0, s[10:11]
	v_lshl_add_u64 v[24:25], v[24:25], 0, s[10:11]
	v_lshl_add_u64 v[26:27], v[26:27], 0, s[10:11]
	v_lshl_add_u64 v[12:13], v[10:11], 0, v[12:13]
	v_lshl_add_u64 v[14:15], v[10:11], 0, v[14:15]
	v_lshl_add_u64 v[16:17], v[10:11], 0, v[16:17]
	v_lshl_add_u64 v[18:19], v[10:11], 0, v[18:19]
	v_lshl_add_u64 v[20:21], v[10:11], 0, v[20:21]
	v_lshl_add_u64 v[22:23], v[10:11], 0, v[22:23]
	v_lshl_add_u64 v[24:25], v[10:11], 0, v[24:25]
	v_lshl_add_u64 v[26:27], v[10:11], 0, v[26:27]
	s_mov_b64 s[10:11], 0
	v_mov_b32_e32 v4, v38
	v_lshl_add_u64 v[46:47], v[26:27], 0, s[10:11]
	v_lshl_add_u64 v[48:49], v[24:25], 0, s[10:11]
	v_lshl_add_u64 v[50:51], v[22:23], 0, s[10:11]
	v_lshl_add_u64 v[52:53], v[20:21], 0, s[10:11]
	v_lshl_add_u64 v[54:55], v[18:19], 0, s[10:11]
	v_lshl_add_u64 v[56:57], v[16:17], 0, s[10:11]
	v_lshl_add_u64 v[58:59], v[14:15], 0, s[10:11]
	v_lshl_add_u64 v[60:61], v[12:13], 0, s[10:11]
	global_load_dword v70, v[46:47], off nt
	global_load_dword v71, v[48:49], off nt
	global_load_dword v72, v[50:51], off nt
	global_load_dword v73, v[52:53], off nt
	global_load_dword v74, v[54:55], off nt
	global_load_dword v75, v[56:57], off nt
	global_load_dword v76, v[58:59], off nt
	global_load_dword v77, v[60:61], off nt
	s_add_u32 s10, s10, 0x80000
	s_addc_u32 s11, s11, 0
	v_lshl_add_u64 v[46:47], v[26:27], 0, s[10:11]
	v_lshl_add_u64 v[48:49], v[24:25], 0, s[10:11]
	v_lshl_add_u64 v[50:51], v[22:23], 0, s[10:11]
	v_lshl_add_u64 v[52:53], v[20:21], 0, s[10:11]
	v_lshl_add_u64 v[54:55], v[18:19], 0, s[10:11]
	v_lshl_add_u64 v[56:57], v[16:17], 0, s[10:11]
	v_lshl_add_u64 v[58:59], v[14:15], 0, s[10:11]
	v_lshl_add_u64 v[60:61], v[12:13], 0, s[10:11]
	global_load_dword v78, v[46:47], off nt
	global_load_dword v79, v[48:49], off nt
	global_load_dword v80, v[50:51], off nt
	global_load_dword v81, v[52:53], off nt
	global_load_dword v82, v[54:55], off nt
	global_load_dword v83, v[56:57], off nt
	global_load_dword v84, v[58:59], off nt
	global_load_dword v85, v[60:61], off nt
	s_add_u32 s10, s10, 0x80000
	s_addc_u32 s11, s11, 0
	v_lshl_add_u64 v[46:47], v[26:27], 0, s[10:11]
; #define LAS __attribute__((address_space(3)))
; __device__ __forceinline__ unsigned cvtpk(float lo, float hi) { unsigned r; asm volatile("v_cvt_pk_bf16_f32 %0, %1, %2" : "=v"(r) : "v"(lo), "v"(hi)); return r; }
; __device__ __forceinline__ void transpose_item(const float* W, int K, int N, bf16_t* WT, LAS float* scr, int item, int lane, int perm_below) {
;     const int nblk = N / 32, kb = item / nblk, nb = item % nblk, k0 = 64 * kb, n0 = 32 * nb;
; #pragma unroll 8
;     for (int i = 0; i < 32; ++i) { const int kk = 2 * i + (lane >> 5); scr[kk * 33 + (lane & 31)] = __builtin_nontemporal_load(W + (size_t)(k0 + kk) * N + n0 + (lane & 31)); }
;     asm volatile("s_waitcnt lgkmcnt(0)" ::: "memory");
;     const int c = lane & 7; const bool pr = n0 < perm_below;
; #pragma unroll
;     for (int j = 0; j < 4; ++j) { const int n = (lane >> 3) + 8 * j; const int ns = pr ? pg8::perm32inv(n) : n; const LAS float* s = scr + (8 * c) * 33 + ns;
;         u32x4 o; o.x = cvtpk(s[0 * 33], s[1 * 33]); o.y = cvtpk(s[2 * 33], s[3 * 33]); o.z = cvtpk(s[4 * 33], s[5 * 33]); o.w = cvtpk(s[6 * 33], s[7 * 33]);
;         *(u32x4*)(WT + (size_t)(n0 + n) * K + k0 + 8 * c) = o; }
	v_lshl_add_u64 v[48:49], v[24:25], 0, s[10:11]
	v_lshl_add_u64 v[50:51], v[22:23], 0, s[10:11]
	v_lshl_add_u64 v[52:53], v[20:21], 0, s[10:11]
	v_lshl_add_u64 v[54:55], v[18:19], 0, s[10:11]
	v_lshl_add_u64 v[56:57], v[16:17], 0, s[10:11]
	v_lshl_add_u64 v[58:59], v[14:15], 0, s[10:11]
	v_lshl_add_u64 v[60:61], v[12:13], 0, s[10:11]
	global_load_dword v86, v[46:47], off nt
	global_load_dword v87, v[48:49], off nt
	global_load_dword v88, v[50:51], off nt
	global_load_dword v89, v[52:53], off nt
	global_load_dword v90, v[54:55], off nt
	global_load_dword v91, v[56:57], off nt
	global_load_dword v92, v[58:59], off nt
	global_load_dword v93, v[60:61], off nt
	s_add_u32 s10, s10, 0x80000
	s_addc_u32 s11, s11, 0
	v_lshl_add_u64 v[46:47], v[26:27], 0, s[10:11]
	v_lshl_add_u64 v[48:49], v[24:25], 0, s[10:11]
	v_lshl_add_u64 v[50:51], v[22:23], 0, s[10:11]
	v_lshl_add_u64 v[52:53], v[20:21], 0, s[10:11]
	v_lshl_add_u64 v[54:55], v[18:19], 0, s[10:11]
	v_lshl_add_u64 v[56:57], v[16:17], 0, s[10:11]
	v_lshl_add_u64 v[58:59], v[14:15], 0, s[10:11]
	v_lshl_add_u64 v[60:61], v[12:13], 0, s[10:11]
	global_load_dword v94, v[46:47], off nt
	global_load_dword v95, v[48:49], off nt
	global_load_dword v96, v[50:51], off nt
	global_load_dword v97, v[52:53], off nt
	global_load_dword v98, v[54:55], off nt
	global_load_dword v99, v[56:57], off nt
	global_load_dword v100, v[58:59], off nt
	global_load_dword v101, v[60:61], off nt
	s_add_u32 s10, s10, 0x80000
	s_addc_u32 s11, s11, 0
	v_add_u32_e32 v46, 0x400, v4
	s_waitcnt vmcnt(30)
	ds_write2_b32 v4, v70, v71 offset1:66
	s_waitcnt vmcnt(28)
	ds_write2_b32 v4, v72, v73 offset0:132 offset1:198
	s_waitcnt vmcnt(26)
	ds_write2_b32 v46, v74, v75 offset0:8 offset1:74
	s_waitcnt vmcnt(24)
	ds_write2_b32 v46, v76, v77 offset0:140 offset1:206
	v_add_u32_e32 v4, 0x840, v4
	v_add_u32_e32 v46, 0x400, v4
	s_waitcnt vmcnt(22)
	ds_write2_b32 v4, v78, v79 offset1:66
	s_waitcnt vmcnt(20)
	ds_write2_b32 v4, v80, v81 offset0:132 offset1:198
	s_waitcnt vmcnt(18)
	ds_write2_b32 v46, v82, v83 offset0:8 offset1:74
	s_waitcnt vmcnt(16)
	ds_write2_b32 v46, v84, v85 offset0:140 offset1:206
	v_add_u32_e32 v4, 0x840, v4
	v_add_u32_e32 v46, 0x400, v4
	s_waitcnt vmcnt(14)
	ds_write2_b32 v4, v86, v87 offset1:66
	s_waitcnt vmcnt(12)
	ds_write2_b32 v4, v88, v89 offset0:132 offset1:198
	s_waitcnt vmcnt(10)
	ds_write2_b32 v46, v90, v91 offset0:8 offset1:74
	s_waitcnt vmcnt(8)
	ds_write2_b32 v46, v92, v93 offset0:140 offset1:206
	v_add_u32_e32 v4, 0x840, v4
	v_add_u32_e32 v46, 0x400, v4
	s_waitcnt vmcnt(6)
	ds_write2_b32 v4, v94, v95 offset1:66
	s_waitcnt vmcnt(4)
	ds_write2_b32 v4, v96, v97 offset0:132 offset1:198
	s_waitcnt vmcnt(2)
	ds_write2_b32 v46, v98, v99 offset0:8 offset1:74
	s_waitcnt vmcnt(0)
	ds_write2_b32 v46, v100, v101 offset0:140 offset1:206
	v_add_u32_e32 v4, 0x840, v4
	s_cmp_lt_i32 s0, 64
	s_cselect_b64 vcc, -1, 0
	v_cndmask_b32_e32 v4, v29, v34, vcc
	s_waitcnt lgkmcnt(0)
	v_lshl_add_u32 v4, v4, 2, v1
	ds_read2_b32 v[12:13], v4 offset1:33
	s_waitcnt lgkmcnt(0)
	v_cvt_pk_bf16_f32 v12, v12, v13
	ds_read2_b32 v[14:15], v4 offset0:66 offset1:99
	s_waitcnt lgkmcnt(0)
	v_cvt_pk_bf16_f32 v13, v14, v15
	ds_read2_b32 v[14:15], v4 offset0:132 offset1:165
	v_or_b32_e32 v16, s6, v29
	s_waitcnt lgkmcnt(0)
	v_cvt_pk_bf16_f32 v14, v14, v15
	ds_read2_b32 v[18:19], v4 offset0:198 offset1:231
	s_ashr_i32 s9, s8, 31
	v_ashrrev_i32_e32 v17, 31, v16
	v_cndmask_b32_e32 v4, v31, v35, vcc
	v_lshl_add_u32 v4, v4, 2, v1
	v_lshl_add_u64 v[20:21], s[8:9], 1, v[8:9]
	v_lshlrev_b64 v[16:17], 12, v[16:17]
	s_waitcnt lgkmcnt(0)
	v_cvt_pk_bf16_f32 v15, v18, v19
	ds_read2_b32 v[18:19], v4 offset1:33
	v_lshl_add_u64 v[16:17], v[20:21], 0, v[16:17]
	global_store_dwordx4 v[16:17], v[12:15], off
	s_waitcnt lgkmcnt(0)
	s_nop 0
	v_cvt_pk_bf16_f32 v12, v18, v19
	ds_read2_b32 v[14:15], v4 offset0:66 offset1:99
	v_or_b32_e32 v18, s6, v31
	s_waitcnt lgkmcnt(0)
	v_cvt_pk_bf16_f32 v13, v14, v15
	ds_read2_b32 v[14:15], v4 offset0:132 offset1:165
	v_ashrrev_i32_e32 v19, 31, v18
	s_waitcnt lgkmcnt(0)
	v_cvt_pk_bf16_f32 v14, v14, v15
	ds_read2_b32 v[16:17], v4 offset0:198 offset1:231
	v_cndmask_b32_e32 v4, v32, v36, vcc
	v_lshlrev_b64 v[18:19], 12, v[18:19]
	v_lshl_add_u32 v4, v4, 2, v1
	s_waitcnt lgkmcnt(0)
	v_cvt_pk_bf16_f32 v15, v16, v17
	v_lshl_add_u64 v[18:19], v[20:21], 0, v[18:19]
	ds_read2_b32 v[16:17], v4 offset1:33
	global_store_dwordx4 v[18:19], v[12:15], off
	v_or_b32_e32 v18, s6, v32
	v_ashrrev_i32_e32 v19, 31, v18
	s_waitcnt lgkmcnt(0)
	v_cvt_pk_bf16_f32 v12, v16, v17
	ds_read2_b32 v[14:15], v4 offset0:66 offset1:99
	s_waitcnt lgkmcnt(0)
	v_cvt_pk_bf16_f32 v13, v14, v15
	ds_read2_b32 v[14:15], v4 offset0:132 offset1:165
	s_waitcnt lgkmcnt(0)
	v_cvt_pk_bf16_f32 v14, v14, v15
	ds_read2_b32 v[16:17], v4 offset0:198 offset1:231
	v_cndmask_b32_e32 v4, v33, v37, vcc
	v_lshlrev_b64 v[18:19], 12, v[18:19]
	v_lshl_add_u32 v4, v4, 2, v1
	s_waitcnt lgkmcnt(0)
	v_cvt_pk_bf16_f32 v15, v16, v17
	v_lshl_add_u64 v[18:19], v[20:21], 0, v[18:19]
	ds_read2_b32 v[16:17], v4 offset1:33
	global_store_dwordx4 v[18:19], v[12:15], off
	v_or_b32_e32 v18, s6, v33
	v_ashrrev_i32_e32 v19, 31, v18
	s_waitcnt lgkmcnt(0)
	v_cvt_pk_bf16_f32 v12, v16, v17
	ds_read2_b32 v[14:15], v4 offset0:66 offset1:99
	s_waitcnt lgkmcnt(0)
	v_cvt_pk_bf16_f32 v13, v14, v15
	ds_read2_b32 v[14:15], v4 offset0:132 offset1:165
	s_waitcnt lgkmcnt(0)
	v_cvt_pk_bf16_f32 v14, v14, v15
	ds_read2_b32 v[16:17], v4 offset0:198 offset1:231
	v_lshlrev_b64 v[18:19], 12, v[18:19]
	s_waitcnt lgkmcnt(0)
	v_cvt_pk_bf16_f32 v15, v16, v17
	v_lshl_add_u64 v[16:17], v[20:21], 0, v[18:19]
	global_store_dwordx4 v[16:17], v[12:15], off
	s_waitcnt lgkmcnt(0)
	s_branch .LBB0_38
